# v99 with same-accumulator MFMAs issued back to back in the diff and MLA attention streams (S0 chain, S1 chain, PV d-tile-major); re-anchor temporaries moved off the K address registers
# speedup vs baseline: 1.0004x; 1.0004x over previous
.Lmv_h1a_fast:
	v_add_f32_e32 v183, v183, v157
	v_lshl_add_u32 v0, s12, 14, v159
	s_add_i32 s0, s35, 0xffffc000
	s_and_b32 s0, s0, 0x4000
	v_add_u32_e32 v154, s0, v190
	v_add_u32_e32 v210, v0, v184
	v_add_u32_e32 v211, v0, v185
	v_add_u32_e32 v212, v0, v186
	v_add_u32_e32 v213, v0, v187
	v_add_u32_e32 v214, v0, v188
	v_add_u32_e32 v215, v0, v189
	v_add_u32_e32 v216, v154, v191
	v_add_u32_e32 v217, v154, v192
	v_add_u32_e32 v196, v154, v193
	v_add_u32_e32 v197, v154, v194
	ds_read_b128 v[98:101], v210
	ds_read_b128 v[102:105], v211
	ds_read_b128 v[106:109], v212
	ds_read_b128 v[110:113], v213
	s_barrier
	s_setprio 1
	s_waitcnt lgkmcnt(3)
	v_mfma_f32_32x32x16_bf16 v[66:81], v[98:101], v[114:117], v[34:49]
	ds_read_b128 v[98:101], v214
	s_waitcnt lgkmcnt(3)
	v_mfma_f32_32x32x16_bf16 v[66:81], v[102:105], v[118:121], v[66:81]
	ds_read_b128 v[102:105], v215
	s_waitcnt lgkmcnt(3)
	v_mfma_f32_32x32x16_bf16 v[66:81], v[106:109], v[122:125], v[66:81]
	ds_read_b128 v[106:109], v210 offset:8192
	s_waitcnt lgkmcnt(3)
	v_mfma_f32_32x32x16_bf16 v[66:81], v[110:113], v[126:129], v[66:81]
	ds_read_b128 v[110:113], v211 offset:8192
	s_waitcnt lgkmcnt(3)
	v_mfma_f32_32x32x16_bf16 v[66:81], v[98:101], v[130:133], v[66:81]
	ds_read_b128 v[98:101], v212 offset:8192
	s_waitcnt lgkmcnt(3)
	v_mfma_f32_32x32x16_bf16 v[66:81], v[102:105], v[134:137], v[66:81]
	ds_read_b128 v[102:105], v213 offset:8192
	s_waitcnt lgkmcnt(3)
	v_mfma_f32_32x32x16_bf16 v[50:65], v[106:109], v[114:117], v[34:49]
	ds_read_b128 v[106:109], v214 offset:8192
	s_waitcnt lgkmcnt(3)
	v_mfma_f32_32x32x16_bf16 v[50:65], v[110:113], v[118:121], v[50:65]
	ds_read_b128 v[110:113], v215 offset:8192
	s_waitcnt lgkmcnt(3)
	v_mfma_f32_32x32x16_bf16 v[50:65], v[98:101], v[122:125], v[50:65]
	ds_read_b128 v[98:101], v216
	s_waitcnt lgkmcnt(3)
	v_mfma_f32_32x32x16_bf16 v[50:65], v[102:105], v[126:129], v[50:65]
	ds_read_b128 v[102:105], v217
	s_waitcnt lgkmcnt(3)
	v_mfma_f32_32x32x16_bf16 v[50:65], v[106:109], v[130:133], v[50:65]
	ds_read_b128 v[106:109], v196
	s_waitcnt lgkmcnt(3)
	v_mfma_f32_32x32x16_bf16 v[50:65], v[110:113], v[134:137], v[50:65]
	ds_read_b128 v[110:113], v197
	s_waitcnt lgkmcnt(3)
	v_mfma_f32_32x32x16_bf16 v[2:17], v[98:101], v[82:85], v[2:17]
	ds_read_b128 v[98:101], v216 offset:4096
	s_waitcnt lgkmcnt(3)
	v_mfma_f32_32x32x16_bf16 v[2:17], v[102:105], v[86:89], v[2:17]
	ds_read_b128 v[102:105], v217 offset:4096
	s_waitcnt lgkmcnt(3)
	v_mfma_f32_32x32x16_bf16 v[2:17], v[106:109], v[90:93], v[2:17]
	ds_read_b128 v[106:109], v196 offset:4096
	s_waitcnt lgkmcnt(3)
	v_mfma_f32_32x32x16_bf16 v[2:17], v[110:113], v[94:97], v[2:17]
	ds_read_b128 v[110:113], v197 offset:4096
	s_waitcnt lgkmcnt(3)
	v_mfma_f32_32x32x16_bf16 v[18:33], v[98:101], v[82:85], v[18:33]
	s_waitcnt lgkmcnt(2)
	v_mfma_f32_32x32x16_bf16 v[18:33], v[102:105], v[86:89], v[18:33]
	s_waitcnt lgkmcnt(1)
	v_mfma_f32_32x32x16_bf16 v[18:33], v[106:109], v[90:93], v[18:33]
	s_waitcnt lgkmcnt(0)
	v_mfma_f32_32x32x16_bf16 v[18:33], v[110:113], v[94:97], v[18:33]
	s_setprio 0
	s_barrier
	s_cmp_ge_u32 s36, s34
	s_cbranch_scc1 .Lmv1_skip1
	s_and_b32 s0, s35, 0x4000
	s_add_i32 m0, s27, s0
	v_lshl_add_u64 v[198:199], s[84:85], 0, v[176:177]
	v_lshl_add_u64 v[198:199], v[198:199], 0, s[78:79]
	global_load_lds_dwordx4 v[198:199], off

.Lmv_h1b_fast:
	v_add_f32_e32 v183, v183, v157
	s_add_i32 s8, s8, 0x8000
	s_and_b32 s0, s8, 0x8000
	v_add_u32_e32 v0, s0, v159
	v_lshl_add_u32 v154, s12, 13, v190
	v_add_u32_e32 v210, v0, v184
	v_add_u32_e32 v211, v0, v185
	v_add_u32_e32 v212, v0, v186
	v_add_u32_e32 v213, v0, v187
	v_add_u32_e32 v214, v0, v188
	v_add_u32_e32 v215, v0, v189
	v_add_u32_e32 v216, v154, v191
	v_add_u32_e32 v217, v154, v192
	v_add_u32_e32 v196, v154, v193
	v_add_u32_e32 v197, v154, v194
	ds_read_b128 v[98:101], v210
	ds_read_b128 v[102:105], v211
	ds_read_b128 v[106:109], v212
	ds_read_b128 v[110:113], v213
	s_barrier
	s_setprio 1
	s_waitcnt lgkmcnt(3)
	v_mfma_f32_32x32x16_bf16 v[66:81], v[98:101], v[114:117], v[34:49]
	ds_read_b128 v[98:101], v214
	s_waitcnt lgkmcnt(3)
	v_mfma_f32_32x32x16_bf16 v[66:81], v[102:105], v[118:121], v[66:81]
	ds_read_b128 v[102:105], v215
	s_waitcnt lgkmcnt(3)
	v_mfma_f32_32x32x16_bf16 v[66:81], v[106:109], v[122:125], v[66:81]
	ds_read_b128 v[106:109], v210 offset:8192
	s_waitcnt lgkmcnt(3)
	v_mfma_f32_32x32x16_bf16 v[66:81], v[110:113], v[126:129], v[66:81]
	ds_read_b128 v[110:113], v211 offset:8192
	s_waitcnt lgkmcnt(3)
	v_mfma_f32_32x32x16_bf16 v[66:81], v[98:101], v[130:133], v[66:81]
	ds_read_b128 v[98:101], v212 offset:8192
	s_waitcnt lgkmcnt(3)
	v_mfma_f32_32x32x16_bf16 v[66:81], v[102:105], v[134:137], v[66:81]
	ds_read_b128 v[102:105], v213 offset:8192
	s_waitcnt lgkmcnt(3)
	v_mfma_f32_32x32x16_bf16 v[50:65], v[106:109], v[114:117], v[34:49]
	ds_read_b128 v[106:109], v214 offset:8192
	s_waitcnt lgkmcnt(3)
	v_mfma_f32_32x32x16_bf16 v[50:65], v[110:113], v[118:121], v[50:65]
	ds_read_b128 v[110:113], v215 offset:8192
	s_waitcnt lgkmcnt(3)
	v_mfma_f32_32x32x16_bf16 v[50:65], v[98:101], v[122:125], v[50:65]
	ds_read_b128 v[98:101], v216
	s_waitcnt lgkmcnt(3)
	v_mfma_f32_32x32x16_bf16 v[50:65], v[102:105], v[126:129], v[50:65]
	ds_read_b128 v[102:105], v217
	s_waitcnt lgkmcnt(3)
	v_mfma_f32_32x32x16_bf16 v[50:65], v[106:109], v[130:133], v[50:65]
	ds_read_b128 v[106:109], v196
	s_waitcnt lgkmcnt(3)
	v_mfma_f32_32x32x16_bf16 v[50:65], v[110:113], v[134:137], v[50:65]
	ds_read_b128 v[110:113], v197
	s_waitcnt lgkmcnt(3)
	v_mfma_f32_32x32x16_bf16 v[2:17], v[98:101], v[82:85], v[2:17]
	ds_read_b128 v[98:101], v216 offset:4096
	s_waitcnt lgkmcnt(3)
	v_mfma_f32_32x32x16_bf16 v[2:17], v[102:105], v[86:89], v[2:17]
	ds_read_b128 v[102:105], v217 offset:4096
	s_waitcnt lgkmcnt(3)
	v_mfma_f32_32x32x16_bf16 v[2:17], v[106:109], v[90:93], v[2:17]
	ds_read_b128 v[106:109], v196 offset:4096
	s_waitcnt lgkmcnt(3)
	v_mfma_f32_32x32x16_bf16 v[2:17], v[110:113], v[94:97], v[2:17]
	ds_read_b128 v[110:113], v197 offset:4096
	s_waitcnt lgkmcnt(3)
	v_mfma_f32_32x32x16_bf16 v[18:33], v[98:101], v[82:85], v[18:33]
	s_waitcnt lgkmcnt(2)
	v_mfma_f32_32x32x16_bf16 v[18:33], v[102:105], v[86:89], v[18:33]
	s_waitcnt lgkmcnt(1)
	v_mfma_f32_32x32x16_bf16 v[18:33], v[106:109], v[90:93], v[18:33]
	s_waitcnt lgkmcnt(0)
	v_mfma_f32_32x32x16_bf16 v[18:33], v[110:113], v[94:97], v[18:33]
	s_setprio 0
	s_branch .Lmjoin
.Lmh0:
	v_lshl_add_u32 v0, s12, 14, v159
	s_add_i32 s0, s35, 0xffffc000
	s_and_b32 s0, s0, 0x4000
	v_add_u32_e32 v154, s0, v190
	v_add_u32_e32 v210, v0, v184
	v_add_u32_e32 v211, v0, v185
	v_add_u32_e32 v212, v0, v186
	v_add_u32_e32 v213, v0, v187
	v_add_u32_e32 v214, v0, v188
	v_add_u32_e32 v215, v0, v189
	v_add_u32_e32 v216, v154, v191
	v_add_u32_e32 v217, v154, v192
	v_add_u32_e32 v196, v154, v193
	v_add_u32_e32 v197, v154, v194
	ds_read_b128 v[98:101], v210
	ds_read_b128 v[102:105], v211
	ds_read_b128 v[106:109], v212
	ds_read_b128 v[110:113], v213
	s_setprio 1
	s_waitcnt lgkmcnt(3)
	v_mfma_f32_32x32x16_bf16 v[66:81], v[98:101], v[114:117], v[34:49]
	ds_read_b128 v[98:101], v214
	s_waitcnt lgkmcnt(3)
	v_mfma_f32_32x32x16_bf16 v[66:81], v[102:105], v[118:121], v[66:81]
	ds_read_b128 v[102:105], v215
	s_waitcnt lgkmcnt(3)
	v_mfma_f32_32x32x16_bf16 v[66:81], v[106:109], v[122:125], v[66:81]
	ds_read_b128 v[106:109], v210 offset:8192
	s_waitcnt lgkmcnt(3)
	v_mfma_f32_32x32x16_bf16 v[66:81], v[110:113], v[126:129], v[66:81]
	ds_read_b128 v[110:113], v211 offset:8192
	s_waitcnt lgkmcnt(3)
	v_mfma_f32_32x32x16_bf16 v[66:81], v[98:101], v[130:133], v[66:81]
	ds_read_b128 v[98:101], v212 offset:8192
	s_waitcnt lgkmcnt(3)
	v_mfma_f32_32x32x16_bf16 v[66:81], v[102:105], v[134:137], v[66:81]
	ds_read_b128 v[102:105], v213 offset:8192
	s_waitcnt lgkmcnt(3)
	v_mfma_f32_32x32x16_bf16 v[50:65], v[106:109], v[114:117], v[34:49]
	ds_read_b128 v[106:109], v214 offset:8192
	s_waitcnt lgkmcnt(3)
	v_mfma_f32_32x32x16_bf16 v[50:65], v[110:113], v[118:121], v[50:65]
	ds_read_b128 v[110:113], v215 offset:8192
	s_waitcnt lgkmcnt(3)
	v_mfma_f32_32x32x16_bf16 v[50:65], v[98:101], v[122:125], v[50:65]
	ds_read_b128 v[98:101], v216
	s_waitcnt lgkmcnt(3)
	v_mfma_f32_32x32x16_bf16 v[50:65], v[102:105], v[126:129], v[50:65]
	ds_read_b128 v[102:105], v217
	s_waitcnt lgkmcnt(3)
	v_mfma_f32_32x32x16_bf16 v[50:65], v[106:109], v[130:133], v[50:65]
	ds_read_b128 v[106:109], v196
	s_waitcnt lgkmcnt(3)
	v_mfma_f32_32x32x16_bf16 v[50:65], v[110:113], v[134:137], v[50:65]
	ds_read_b128 v[110:113], v197
	s_waitcnt lgkmcnt(3)
	v_mfma_f32_32x32x16_bf16 v[2:17], v[98:101], v[82:85], v[2:17]
	ds_read_b128 v[98:101], v216 offset:4096
	s_waitcnt lgkmcnt(3)
	v_mfma_f32_32x32x16_bf16 v[2:17], v[102:105], v[86:89], v[2:17]
	ds_read_b128 v[102:105], v217 offset:4096
	s_waitcnt lgkmcnt(3)
	v_mfma_f32_32x32x16_bf16 v[2:17], v[106:109], v[90:93], v[2:17]
	ds_read_b128 v[106:109], v196 offset:4096
	s_waitcnt lgkmcnt(3)
	v_mfma_f32_32x32x16_bf16 v[2:17], v[110:113], v[94:97], v[2:17]
	ds_read_b128 v[110:113], v197 offset:4096
	s_waitcnt lgkmcnt(3)
	v_mfma_f32_32x32x16_bf16 v[18:33], v[98:101], v[82:85], v[18:33]
	s_waitcnt lgkmcnt(2)
	v_mfma_f32_32x32x16_bf16 v[18:33], v[102:105], v[86:89], v[18:33]
	s_waitcnt lgkmcnt(1)
	v_mfma_f32_32x32x16_bf16 v[18:33], v[106:109], v[90:93], v[18:33]
	s_waitcnt lgkmcnt(0)
	v_mfma_f32_32x32x16_bf16 v[18:33], v[110:113], v[94:97], v[18:33]
	s_setprio 0
	s_barrier
	s_cmp_ge_u32 s36, s34
	s_cbranch_scc1 .Lmv_skip1
	s_and_b32 s0, s35, 0x4000
	s_add_i32 m0, s27, s0
	v_lshl_add_u64 v[198:199], s[84:85], 0, v[176:177]
	v_lshl_add_u64 v[198:199], v[198:199], 0, s[78:79]
	global_load_lds_dwordx4 v[198:199], off

.Lmv_h0a_fast:
	v_add_f32_e32 v183, v183, v157
	s_add_i32 s8, s8, 0x8000
	s_and_b32 s0, s8, 0x8000
	v_add_u32_e32 v0, s0, v159
	v_lshl_add_u32 v154, s12, 13, v190
	v_add_u32_e32 v210, v0, v184
	v_add_u32_e32 v211, v0, v185
	v_add_u32_e32 v212, v0, v186
	v_add_u32_e32 v213, v0, v187
	v_add_u32_e32 v214, v0, v188
	v_add_u32_e32 v215, v0, v189
	v_add_u32_e32 v216, v154, v191
	v_add_u32_e32 v217, v154, v192
	v_add_u32_e32 v196, v154, v193
	v_add_u32_e32 v197, v154, v194
	ds_read_b128 v[98:101], v210
	ds_read_b128 v[102:105], v211
	ds_read_b128 v[106:109], v212
	ds_read_b128 v[110:113], v213
	s_barrier
	s_setprio 1
	s_waitcnt lgkmcnt(3)
	v_mfma_f32_32x32x16_bf16 v[66:81], v[98:101], v[114:117], v[34:49]
	ds_read_b128 v[98:101], v214
	s_waitcnt lgkmcnt(3)
	v_mfma_f32_32x32x16_bf16 v[66:81], v[102:105], v[118:121], v[66:81]
	ds_read_b128 v[102:105], v215
	s_waitcnt lgkmcnt(3)
	v_mfma_f32_32x32x16_bf16 v[66:81], v[106:109], v[122:125], v[66:81]
	ds_read_b128 v[106:109], v210 offset:8192
	s_waitcnt lgkmcnt(3)
	v_mfma_f32_32x32x16_bf16 v[66:81], v[110:113], v[126:129], v[66:81]
	ds_read_b128 v[110:113], v211 offset:8192
	s_waitcnt lgkmcnt(3)
	v_mfma_f32_32x32x16_bf16 v[66:81], v[98:101], v[130:133], v[66:81]
	ds_read_b128 v[98:101], v212 offset:8192
	s_waitcnt lgkmcnt(3)
	v_mfma_f32_32x32x16_bf16 v[66:81], v[102:105], v[134:137], v[66:81]
	ds_read_b128 v[102:105], v213 offset:8192
	s_waitcnt lgkmcnt(3)
	v_mfma_f32_32x32x16_bf16 v[50:65], v[106:109], v[114:117], v[34:49]
	ds_read_b128 v[106:109], v214 offset:8192
	s_waitcnt lgkmcnt(3)
	v_mfma_f32_32x32x16_bf16 v[50:65], v[110:113], v[118:121], v[50:65]
	ds_read_b128 v[110:113], v215 offset:8192
	s_waitcnt lgkmcnt(3)
	v_mfma_f32_32x32x16_bf16 v[50:65], v[98:101], v[122:125], v[50:65]
	ds_read_b128 v[98:101], v216
	s_waitcnt lgkmcnt(3)
	v_mfma_f32_32x32x16_bf16 v[50:65], v[102:105], v[126:129], v[50:65]
	ds_read_b128 v[102:105], v217
	s_waitcnt lgkmcnt(3)
	v_mfma_f32_32x32x16_bf16 v[50:65], v[106:109], v[130:133], v[50:65]
	ds_read_b128 v[106:109], v196
	s_waitcnt lgkmcnt(3)
	v_mfma_f32_32x32x16_bf16 v[50:65], v[110:113], v[134:137], v[50:65]
	ds_read_b128 v[110:113], v197
	s_waitcnt lgkmcnt(3)
	v_mfma_f32_32x32x16_bf16 v[2:17], v[98:101], v[82:85], v[2:17]
	ds_read_b128 v[98:101], v216 offset:4096
	s_waitcnt lgkmcnt(3)
	v_mfma_f32_32x32x16_bf16 v[2:17], v[102:105], v[86:89], v[2:17]
	ds_read_b128 v[102:105], v217 offset:4096
	s_waitcnt lgkmcnt(3)
	v_mfma_f32_32x32x16_bf16 v[2:17], v[106:109], v[90:93], v[2:17]
	ds_read_b128 v[106:109], v196 offset:4096
	s_waitcnt lgkmcnt(3)
	v_mfma_f32_32x32x16_bf16 v[2:17], v[110:113], v[94:97], v[2:17]
	ds_read_b128 v[110:113], v197 offset:4096
	s_waitcnt lgkmcnt(3)
	v_mfma_f32_32x32x16_bf16 v[18:33], v[98:101], v[82:85], v[18:33]
	s_waitcnt lgkmcnt(2)
	v_mfma_f32_32x32x16_bf16 v[18:33], v[102:105], v[86:89], v[18:33]
	s_waitcnt lgkmcnt(1)
	v_mfma_f32_32x32x16_bf16 v[18:33], v[106:109], v[90:93], v[18:33]
	s_waitcnt lgkmcnt(0)
	v_mfma_f32_32x32x16_bf16 v[18:33], v[110:113], v[94:97], v[18:33]
	s_setprio 0
	s_barrier
	s_cmp_ge_u32 s36, s34
	s_cbranch_scc1 .Lmjoin
	s_mov_b64 s[4:5], 0
	s_mov_b64 s[10:11], 0

.Ldv_pre_top:
	v_exp_f32_e32 v238, v98
	v_exp_f32_e32 v222, v82
	v_exp_f32_e32 v239, v99
	v_exp_f32_e32 v223, v83
	v_exp_f32_e32 v240, v100
	v_add_f32_e32 v196, v238, v239
	v_exp_f32_e32 v224, v84
	v_add_f32_e32 v198, v222, v223
	v_exp_f32_e32 v241, v101
	v_add_f32_e32 v196, v240, v196
	v_exp_f32_e32 v225, v85
	v_add_f32_e32 v198, v224, v198
	v_exp_f32_e32 v242, v102
	v_add_f32_e32 v196, v241, v196
	v_exp_f32_e32 v226, v86
	v_add_f32_e32 v198, v225, v198
	v_exp_f32_e32 v243, v103
	v_add_f32_e32 v196, v242, v196
	v_exp_f32_e32 v227, v87
	v_add_f32_e32 v198, v226, v198
	v_exp_f32_e32 v244, v104
	v_add_f32_e32 v196, v243, v196
	v_exp_f32_e32 v228, v88
	v_add_f32_e32 v198, v227, v198
	v_exp_f32_e32 v245, v105
	v_add_f32_e32 v196, v244, v196
	v_exp_f32_e32 v229, v89
	v_add_f32_e32 v198, v228, v198
	v_exp_f32_e32 v246, v106
	v_add_f32_e32 v196, v245, v196
	v_exp_f32_e32 v230, v90
	v_add_f32_e32 v198, v229, v198
	v_exp_f32_e32 v247, v107
	v_add_f32_e32 v196, v246, v196
	v_exp_f32_e32 v231, v91
	v_add_f32_e32 v198, v230, v198
	v_exp_f32_e32 v248, v108
	v_add_f32_e32 v196, v247, v196
	v_exp_f32_e32 v232, v92
	v_add_f32_e32 v198, v231, v198
	v_exp_f32_e32 v249, v109
	v_add_f32_e32 v196, v248, v196
	v_exp_f32_e32 v233, v93
	v_add_f32_e32 v198, v232, v198
	v_exp_f32_e32 v180, v110
	v_add_f32_e32 v196, v249, v196
	v_exp_f32_e32 v234, v94
	v_add_f32_e32 v198, v233, v198
	v_exp_f32_e32 v181, v111
	v_add_f32_e32 v196, v180, v196
	v_exp_f32_e32 v235, v95
	v_add_f32_e32 v198, v234, v198
	v_exp_f32_e32 v182, v112
	v_add_f32_e32 v196, v181, v196
	v_exp_f32_e32 v236, v96
	v_add_f32_e32 v198, v235, v198
	v_exp_f32_e32 v183, v113
	v_add_f32_e32 v196, v182, v196
	v_exp_f32_e32 v237, v97
	v_add_f32_e32 v198, v236, v198
	v_add_f32_e32 v196, v183, v196
	v_add_f32_e32 v198, v237, v198
	v_add_f32_e32 v199, v196, v198
	s_nop 0
	v_cmp_ngt_f32_e32 vcc, s72, v199
	s_nop 1
	s_or_b64 vcc, vcc, s[6:7]
	s_andn2_b64 vcc, vcc, s[8:9]
	s_cbranch_vccz .Ldv_pre_fast
	v_max3_f32 v221, v98, v99, v100
	v_max3_f32 v221, v221, v101, v102
	v_max3_f32 v221, v221, v103, v104
	v_max3_f32 v221, v221, v105, v106
	v_max3_f32 v221, v221, v107, v108
	v_max3_f32 v221, v221, v109, v110
	v_max3_f32 v221, v221, v111, v112
	v_max3_f32 v221, v221, v113, v82
	v_max3_f32 v221, v221, v83, v84
	v_max3_f32 v221, v221, v85, v86
	v_max3_f32 v221, v221, v87, v88
	v_max3_f32 v221, v221, v89, v90
	v_max3_f32 v221, v221, v91, v92
	v_max3_f32 v221, v221, v93, v94
	v_max3_f32 v221, v221, v95, v96
	v_max_f32_e32 v221, v221, v97
	ds_bpermute_b32 v196, v173, v221
	s_waitcnt lgkmcnt(0)
	v_max_f32_e32 v221, v221, v196
	s_and_b64 vcc, exec, s[6:7]
	s_cbranch_vccnz .Ldv_pre_anchor
	v_max_f32_e32 v221, 0, v221
	v_exp_f32_e64 v198, -v221
	s_nop 7
	s_nop 7
	v_mul_f32_e32 v197, v197, v198
	v_mul_f32_e32 v2, v2, v198
	v_mul_f32_e32 v3, v3, v198
	v_mul_f32_e32 v4, v4, v198
	v_mul_f32_e32 v5, v5, v198
	v_mul_f32_e32 v6, v6, v198
	v_mul_f32_e32 v7, v7, v198
	v_mul_f32_e32 v8, v8, v198
	v_mul_f32_e32 v9, v9, v198
	v_mul_f32_e32 v10, v10, v198
	v_mul_f32_e32 v11, v11, v198
	v_mul_f32_e32 v12, v12, v198
	v_mul_f32_e32 v13, v13, v198
	v_mul_f32_e32 v14, v14, v198
	v_mul_f32_e32 v15, v15, v198
	v_mul_f32_e32 v16, v16, v198
	v_mul_f32_e32 v17, v17, v198
	v_mul_f32_e32 v50, v50, v198
	v_mul_f32_e32 v51, v51, v198
	v_mul_f32_e32 v52, v52, v198
	v_mul_f32_e32 v53, v53, v198
	v_mul_f32_e32 v54, v54, v198
	v_mul_f32_e32 v55, v55, v198
	v_mul_f32_e32 v56, v56, v198
	v_mul_f32_e32 v57, v57, v198
	v_mul_f32_e32 v58, v58, v198
	v_mul_f32_e32 v59, v59, v198
	v_mul_f32_e32 v60, v60, v198
	v_mul_f32_e32 v61, v61, v198
	v_mul_f32_e32 v62, v62, v198
	v_mul_f32_e32 v63, v63, v198
	v_mul_f32_e32 v64, v64, v198
	v_mul_f32_e32 v65, v65, v198
	v_mul_f32_e32 v34, v34, v198
	v_mul_f32_e32 v35, v35, v198
	v_mul_f32_e32 v36, v36, v198
	v_mul_f32_e32 v37, v37, v198
	v_mul_f32_e32 v38, v38, v198
	v_mul_f32_e32 v39, v39, v198
	v_mul_f32_e32 v40, v40, v198
	v_mul_f32_e32 v41, v41, v198
	v_mul_f32_e32 v42, v42, v198
	v_mul_f32_e32 v43, v43, v198
	v_mul_f32_e32 v44, v44, v198
	v_mul_f32_e32 v45, v45, v198
	v_mul_f32_e32 v46, v46, v198
	v_mul_f32_e32 v47, v47, v198
	v_mul_f32_e32 v48, v48, v198
	v_mul_f32_e32 v49, v49, v198
	v_mul_f32_e32 v18, v18, v198
	v_mul_f32_e32 v19, v19, v198
	v_mul_f32_e32 v20, v20, v198
	v_mul_f32_e32 v21, v21, v198
	v_mul_f32_e32 v22, v22, v198
	v_mul_f32_e32 v23, v23, v198
	v_mul_f32_e32 v24, v24, v198
	v_mul_f32_e32 v25, v25, v198
	v_mul_f32_e32 v26, v26, v198
	v_mul_f32_e32 v27, v27, v198
	v_mul_f32_e32 v28, v28, v198
	v_mul_f32_e32 v29, v29, v198
	v_mul_f32_e32 v30, v30, v198
	v_mul_f32_e32 v31, v31, v198
	v_mul_f32_e32 v32, v32, v198
	v_mul_f32_e32 v33, v33, v198

.Ldk_skip2:
	v_lshl_add_u32 v196, s11, 13, v211
	s_add_i32 s0, s40, 0xffff8000
	s_and_b32 s0, s0, 0x8000
	v_add_u32_e32 v221, s0, v216
	v_add_u32_e32 v162, v196, v212
	v_add_u32_e32 v163, v196, v213
	v_add_u32_e32 v164, v196, v214
	v_add_u32_e32 v165, v196, v215
	v_add_u32_e32 v166, v221, v217
	v_add_u32_e32 v167, v221, v218
	v_add_u32_e32 v168, v221, v219
	v_add_u32_e32 v169, v221, v220
	ds_read_b128 v[130:133], v162
	ds_read_b128 v[134:137], v163
	ds_read_b128 v[138:141], v164
	ds_read_b128 v[142:145], v165
	v_readlane_b32 s0, v252, 7
	s_cmpk_lt_u32 s0, 0x100
	s_cbranch_scc1 .Ldtop_skip
	s_cmp_eq_u32 s41, 2
	s_cselect_b64 s[6:7], -1, 0
	s_mov_b64 s[8:9], 0

.Ldtop_skip:
	s_setprio 1
	s_waitcnt lgkmcnt(3)
	v_mfma_f32_32x32x16_bf16 v[98:113], v[130:133], v[146:149], v[66:81]
	ds_read_b128 v[130:133], v162 offset:4096
	s_waitcnt lgkmcnt(3)
	v_mfma_f32_32x32x16_bf16 v[98:113], v[134:137], v[150:153], v[98:113]
	ds_read_b128 v[134:137], v163 offset:4096
	s_waitcnt lgkmcnt(3)
	v_mfma_f32_32x32x16_bf16 v[98:113], v[138:141], v[154:157], v[98:113]
	ds_read_b128 v[138:141], v164 offset:4096
	s_waitcnt lgkmcnt(3)
	v_mfma_f32_32x32x16_bf16 v[98:113], v[142:145], v[158:161], v[98:113]
	ds_read_b128 v[142:145], v165 offset:4096
	s_waitcnt lgkmcnt(3)
	v_mfma_f32_32x32x16_bf16 v[82:97], v[130:133], v[146:149], v[66:81]
	ds_read_b128 v[130:133], v166 offset:32768
	s_waitcnt lgkmcnt(3)
	v_mfma_f32_32x32x16_bf16 v[82:97], v[134:137], v[150:153], v[82:97]
	ds_read_b128 v[134:137], v167 offset:32768
	s_waitcnt lgkmcnt(3)
	v_mfma_f32_32x32x16_bf16 v[82:97], v[138:141], v[154:157], v[82:97]
	ds_read_b128 v[138:141], v168 offset:32768
	s_waitcnt lgkmcnt(3)
	v_mfma_f32_32x32x16_bf16 v[82:97], v[142:145], v[158:161], v[82:97]
	ds_read_b128 v[142:145], v169 offset:32768
	s_waitcnt lgkmcnt(3)
	v_mfma_f32_32x32x16_bf16 v[2:17], v[130:133], v[114:117], v[2:17]
	ds_read_b128 v[130:133], v166 offset:36864
	s_waitcnt lgkmcnt(3)
	v_mfma_f32_32x32x16_bf16 v[2:17], v[134:137], v[118:121], v[2:17]
	ds_read_b128 v[134:137], v167 offset:36864
	s_waitcnt lgkmcnt(3)
	v_mfma_f32_32x32x16_bf16 v[2:17], v[138:141], v[122:125], v[2:17]
	ds_read_b128 v[138:141], v168 offset:36864
	s_waitcnt lgkmcnt(3)
	v_mfma_f32_32x32x16_bf16 v[2:17], v[142:145], v[126:129], v[2:17]
	ds_read_b128 v[142:145], v169 offset:36864
	s_waitcnt lgkmcnt(3)
	v_mfma_f32_32x32x16_bf16 v[50:65], v[130:133], v[114:117], v[50:65]
	ds_read_b128 v[130:133], v166 offset:40960
	s_waitcnt lgkmcnt(3)
	v_mfma_f32_32x32x16_bf16 v[50:65], v[134:137], v[118:121], v[50:65]
	ds_read_b128 v[134:137], v167 offset:40960
	s_waitcnt lgkmcnt(3)
	v_mfma_f32_32x32x16_bf16 v[50:65], v[138:141], v[122:125], v[50:65]
	ds_read_b128 v[138:141], v168 offset:40960
	s_waitcnt lgkmcnt(3)
	v_mfma_f32_32x32x16_bf16 v[50:65], v[142:145], v[126:129], v[50:65]
	ds_read_b128 v[142:145], v169 offset:40960
	s_waitcnt lgkmcnt(3)
	v_mfma_f32_32x32x16_bf16 v[34:49], v[130:133], v[114:117], v[34:49]
	ds_read_b128 v[130:133], v166 offset:45056
	s_waitcnt lgkmcnt(3)
	v_mfma_f32_32x32x16_bf16 v[34:49], v[134:137], v[118:121], v[34:49]
	ds_read_b128 v[134:137], v167 offset:45056
	s_waitcnt lgkmcnt(3)
	v_mfma_f32_32x32x16_bf16 v[34:49], v[138:141], v[122:125], v[34:49]
	ds_read_b128 v[138:141], v168 offset:45056
	s_waitcnt lgkmcnt(3)
	v_mfma_f32_32x32x16_bf16 v[34:49], v[142:145], v[126:129], v[34:49]
	ds_read_b128 v[142:145], v169 offset:45056
	s_waitcnt lgkmcnt(3)
	v_mfma_f32_32x32x16_bf16 v[18:33], v[130:133], v[114:117], v[18:33]
	s_waitcnt lgkmcnt(2)
	v_mfma_f32_32x32x16_bf16 v[18:33], v[134:137], v[118:121], v[18:33]
	s_waitcnt lgkmcnt(1)
	v_mfma_f32_32x32x16_bf16 v[18:33], v[138:141], v[122:125], v[18:33]
	s_waitcnt lgkmcnt(0)
	v_mfma_f32_32x32x16_bf16 v[18:33], v[142:145], v[126:129], v[18:33]
	s_setprio 0
	s_addk_i32 s5, 0x4000
	s_and_b32 s0, s5, 0x4000
	v_add_u32_e32 v196, s0, v211
	v_lshl_add_u32 v221, s11, 14, v216
	v_add_u32_e32 v162, v196, v212
	v_add_u32_e32 v163, v196, v213
	v_add_u32_e32 v164, v196, v214
	v_add_u32_e32 v165, v196, v215
	v_add_u32_e32 v166, v221, v217
	v_add_u32_e32 v167, v221, v218
	v_add_u32_e32 v168, v221, v219
	v_add_u32_e32 v169, v221, v220
	ds_read_b128 v[130:133], v162
	ds_read_b128 v[134:137], v163
	ds_read_b128 v[138:141], v164
	ds_read_b128 v[142:145], v165
	s_mov_b64 s[6:7], 0
	s_mov_b64 s[8:9], 0

.Ldv_skip2:
	s_setprio 1
	s_waitcnt lgkmcnt(3)
	v_mfma_f32_32x32x16_bf16 v[98:113], v[130:133], v[146:149], v[66:81]
	ds_read_b128 v[130:133], v162 offset:4096
	s_waitcnt lgkmcnt(3)
	v_mfma_f32_32x32x16_bf16 v[98:113], v[134:137], v[150:153], v[98:113]
	ds_read_b128 v[134:137], v163 offset:4096
	s_waitcnt lgkmcnt(3)
	v_mfma_f32_32x32x16_bf16 v[98:113], v[138:141], v[154:157], v[98:113]
	ds_read_b128 v[138:141], v164 offset:4096
	s_waitcnt lgkmcnt(3)
	v_mfma_f32_32x32x16_bf16 v[98:113], v[142:145], v[158:161], v[98:113]
	ds_read_b128 v[142:145], v165 offset:4096
	s_waitcnt lgkmcnt(3)
	v_mfma_f32_32x32x16_bf16 v[82:97], v[130:133], v[146:149], v[66:81]
	ds_read_b128 v[130:133], v166 offset:32768
	s_waitcnt lgkmcnt(3)
	v_mfma_f32_32x32x16_bf16 v[82:97], v[134:137], v[150:153], v[82:97]
	ds_read_b128 v[134:137], v167 offset:32768
	s_waitcnt lgkmcnt(3)
	v_mfma_f32_32x32x16_bf16 v[82:97], v[138:141], v[154:157], v[82:97]
	ds_read_b128 v[138:141], v168 offset:32768
	s_waitcnt lgkmcnt(3)
	v_mfma_f32_32x32x16_bf16 v[82:97], v[142:145], v[158:161], v[82:97]
	ds_read_b128 v[142:145], v169 offset:32768
	s_waitcnt lgkmcnt(3)
	v_mfma_f32_32x32x16_bf16 v[2:17], v[130:133], v[114:117], v[2:17]
	ds_read_b128 v[130:133], v166 offset:36864
	s_waitcnt lgkmcnt(3)
	v_mfma_f32_32x32x16_bf16 v[2:17], v[134:137], v[118:121], v[2:17]
	ds_read_b128 v[134:137], v167 offset:36864
	s_waitcnt lgkmcnt(3)
	v_mfma_f32_32x32x16_bf16 v[2:17], v[138:141], v[122:125], v[2:17]
	ds_read_b128 v[138:141], v168 offset:36864
	s_waitcnt lgkmcnt(3)
	v_mfma_f32_32x32x16_bf16 v[2:17], v[142:145], v[126:129], v[2:17]
	ds_read_b128 v[142:145], v169 offset:36864
	s_waitcnt lgkmcnt(3)
	v_mfma_f32_32x32x16_bf16 v[50:65], v[130:133], v[114:117], v[50:65]
	ds_read_b128 v[130:133], v166 offset:40960
	s_waitcnt lgkmcnt(3)
	v_mfma_f32_32x32x16_bf16 v[50:65], v[134:137], v[118:121], v[50:65]
	ds_read_b128 v[134:137], v167 offset:40960
	s_waitcnt lgkmcnt(3)
	v_mfma_f32_32x32x16_bf16 v[50:65], v[138:141], v[122:125], v[50:65]
	ds_read_b128 v[138:141], v168 offset:40960
	s_waitcnt lgkmcnt(3)
	v_mfma_f32_32x32x16_bf16 v[50:65], v[142:145], v[126:129], v[50:65]
	ds_read_b128 v[142:145], v169 offset:40960
	s_waitcnt lgkmcnt(3)
	v_mfma_f32_32x32x16_bf16 v[34:49], v[130:133], v[114:117], v[34:49]
	ds_read_b128 v[130:133], v166 offset:45056
	s_waitcnt lgkmcnt(3)
	v_mfma_f32_32x32x16_bf16 v[34:49], v[134:137], v[118:121], v[34:49]
	ds_read_b128 v[134:137], v167 offset:45056
	s_waitcnt lgkmcnt(3)
	v_mfma_f32_32x32x16_bf16 v[34:49], v[138:141], v[122:125], v[34:49]
	ds_read_b128 v[138:141], v168 offset:45056
	s_waitcnt lgkmcnt(3)
	v_mfma_f32_32x32x16_bf16 v[34:49], v[142:145], v[126:129], v[34:49]
	ds_read_b128 v[142:145], v169 offset:45056
	s_waitcnt lgkmcnt(3)
	v_mfma_f32_32x32x16_bf16 v[18:33], v[130:133], v[114:117], v[18:33]
	s_waitcnt lgkmcnt(2)
	v_mfma_f32_32x32x16_bf16 v[18:33], v[134:137], v[118:121], v[18:33]
	s_waitcnt lgkmcnt(1)
	v_mfma_f32_32x32x16_bf16 v[18:33], v[138:141], v[122:125], v[18:33]
	s_waitcnt lgkmcnt(0)
	v_mfma_f32_32x32x16_bf16 v[18:33], v[142:145], v[126:129], v[18:33]
	s_setprio 0
	s_cmp_ge_u32 s41, s30
	s_cbranch_scc1 .Ldend_skip
	v_readlane_b32 s0, v252, 7
	s_cmpk_lt_u32 s0, 0x100
	s_cbranch_scc0 .Ldend_skip
	s_mov_b64 s[6:7], 0
	s_mov_b64 s[8:9], 0
